# gla_scan VT ring for 3 of 4 rotating register sets (the set loaded in the same step as its barrier stays a register load)
# speedup vs baseline: 1.0016x; 1.0016x over previous
; __device__ __forceinline__ void gla_scan(LAS unsigned char* lds, int bx, int G, const bf16_t* KS, const bf16_t* QD, const bf16_t* VT, const float* DEC, bf16_t* Of, bf16_t* Ob) {
;     ...
;         __syncthreads();
;         GLB_LOAD(0, a_); GLB_LOAD(1, b_); GLB_LOAD(2, c_);
;         GLB_LOAD(3, d_); GLB_STEP(0, a_, false);
;         GLB_LOAD(4, a_); GLB_STEP(1, b_, false);
;         GLB_LOAD(5, b_); GLB_STEP(2, c_, false);
;         GLB_LOAD(6, c_); GLB_STEP(3, d_, false);
.LBB0_1280:
	s_bfe_i32 s6, s10, 0x10003
	s_ashr_i32 s18, s10, 4
	s_bfe_u32 s17, s10, 0x10003
	s_and_b32 s13, s6, 3
	s_lshl_b32 s6, s18, 1
	s_or_b32 s19, s6, s17
	s_mul_i32 s11, s19, 36
	s_mul_i32 s12, s18, 36
	s_or_b32 s6, s11, s13
	s_or_b32 s14, s13, s12
	s_ashr_i32 s7, s6, 31
	s_ashr_i32 s15, s14, 31
	s_and_b32 s16, s10, 7
	s_lshl_b64 s[8:9], s[6:7], 14
	s_lshl_b64 s[14:15], s[14:15], 15
	s_add_u32 s14, s54, s14
	s_addc_u32 s15, s55, s15
	v_lshl_or_b32 v182, s16, 12, v211
	s_waitcnt vmcnt(29)
	v_lshl_add_u32 v4, s6, 7, v193
	s_barrier
	v_add_u32_e32 v246, v182, v248
	s_mov_b32 m0, s98
	s_nop 0
	global_load_lds_dwordx4 v246, s[14:15]
	v_ashrrev_i32_e32 v5, 31, v4
	v_lshl_add_u64 v[4:5], v[4:5], 2, s[2:3]
	global_load_dword v30, v[4:5], off
	s_waitcnt vmcnt(18)
	v_lshl_add_u64 v[12:13], v[178:179], 0, s[8:9]
	global_load_dword v251, v249, s[54:55]
	global_load_dwordx4 v[8:11], v[12:13], off
	s_nop 0
	global_load_dwordx4 v[12:15], v[12:13], off offset:1024
	s_nop 0
	global_load_dword v251, v249, s[54:55]
	global_load_dword v251, v249, s[54:55]
	s_add_i32 s6, s17, 1
	s_or_b32 s8, s11, s6
	s_or_b32 s6, s6, s12
	s_ashr_i32 s13, s10, 1
	s_ashr_i32 s9, s8, 31
	s_ashr_i32 s7, s6, 31
	s_andn2_b32 s13, s13, 31
	s_lshl_b64 s[14:15], s[8:9], 14
	s_lshl_b64 s[6:7], s[6:7], 15
	v_lshl_add_u32 v26, s8, 7, v193
	s_add_u32 s20, s54, s6
	v_lshl_add_u64 v[24:25], v[178:179], 0, s[14:15]
	v_ashrrev_i32_e32 v27, 31, v26
	s_addc_u32 s21, s55, s7
	global_load_dwordx4 v[72:75], v[24:25], off
	v_add_u32_e32 v246, v182, v248
	s_mov_b32 m0, s99
	s_nop 0
	global_load_lds_dwordx4 v246, s[20:21]
	global_load_dword v251, v249, s[54:55]
	global_load_dword v251, v249, s[54:55]
	global_load_dword v251, v249, s[54:55]
	v_lshl_add_u64 v[26:27], v[26:27], 2, s[2:3]
	global_load_dwordx4 v[92:95], v[24:25], off offset:1024
	global_load_dword v108, v[26:27], off
	s_sub_i32 s6, 2, s17
	s_or_b32 s22, s11, s6
	s_or_b32 s6, s6, s12
	s_ashr_i32 s23, s22, 31
	s_ashr_i32 s7, s6, 31
	s_lshl_b64 s[24:25], s[22:23], 14
	s_lshl_b64 s[6:7], s[6:7], 15
	s_add_u32 s26, s54, s6
	s_addc_u32 s27, s55, s7
	s_cmp_eq_u32 s17, 0
	s_cselect_b64 s[6:7], -1, 0
	s_and_b64 s[8:9], s[6:7], exec
	v_lshl_add_u64 v[24:25], v[178:179], 0, s[24:25]
	s_cselect_b32 s21, 3, 0
	global_load_dwordx4 v[60:63], v[24:25], off
	global_load_dwordx4 v[56:59], v[24:25], off offset:1024
	v_add_u32_e32 v246, v182, v248
	s_mov_b32 m0, s100
	s_nop 0
	global_load_lds_dwordx4 v246, s[26:27]
	global_load_dword v251, v249, s[54:55]
	global_load_dword v251, v249, s[54:55]
	global_load_dword v251, v249, s[54:55]
	v_lshl_add_u32 v24, s22, 7, v193
	s_cselect_b32 s9, s83, s81
	s_cselect_b32 s8, s82, s80
	s_cselect_b32 s26, 4, 35
	s_cselect_b32 s20, 5, 34
	s_cselect_b32 s17, 6, 33
	s_or_b32 s14, s11, s21
	v_ashrrev_i32_e32 v25, 31, v24
	s_ashr_i32 s15, s14, 31
	v_lshl_add_u64 v[24:25], v[24:25], 2, s[2:3]
	s_lshl_b64 s[22:23], s[14:15], 14
	v_lshl_add_u64 v[28:29], v[178:179], 0, s[22:23]
	global_load_dword v112, v[24:25], off
	global_load_dwordx4 v[120:123], v[28:29], off
	s_or_b32 s22, s21, s12
	s_ashr_i32 s23, s22, 31
	s_lshl_b64 s[22:23], s[22:23], 15
	s_add_u32 s22, s54, s22
	s_addc_u32 s23, s55, s23
	v_add_u32_e32 v246, v182, v248
	s_mov_b32 m0, s101
	s_nop 0
	global_load_lds_dwordx4 v246, s[22:23]
	global_load_dword v251, v249, s[54:55]
	global_load_dword v251, v249, s[54:55]
	global_load_dword v251, v249, s[54:55]
	s_add_i32 s22, s11, s26
	s_ashr_i32 s23, s22, 31
	s_lshl_b64 s[24:25], s[22:23], 14
	v_lshl_add_u64 v[184:185], s[54:55], 0, v[182:183]
	s_waitcnt vmcnt(24)
	v_mul_f32_e32 v24, 0, v30
	v_mov_b32_e32 v25, v24
	v_mov_b32_e32 v26, v24
	v_mov_b32_e32 v27, v24
	s_waitcnt vmcnt(22)
	s_nop 0
	s_waitcnt vmcnt(0)
	s_barrier
	ds_read_b128 v[0:3], v250 offset:0
	ds_read_b128 v[4:7], v250 offset:1024
	ds_read_b128 v[16:19], v250 offset:2048
	ds_read_b128 v[20:23], v250 offset:3072
	ds_read_b128 v[76:79], v250 offset:4096
	ds_read_b128 v[80:83], v250 offset:5120
	ds_read_b128 v[84:87], v250 offset:6144
	ds_read_b128 v[88:91], v250 offset:7168
	s_waitcnt lgkmcnt(0)
	v_mfma_f32_16x16x32_bf16 v[0:3], v[0:3], v[8:11], v[24:27]
	s_waitcnt vmcnt(21)
	v_mfma_f32_16x16x32_bf16 v[104:107], v[4:7], v[12:15], v[0:3]
	v_lshl_add_u32 v4, s14, 7, v193
	v_ashrrev_i32_e32 v5, 31, v4
	v_lshl_add_u64 v[4:5], v[4:5], 2, s[2:3]
	global_load_dwordx4 v[136:139], v[28:29], off offset:1024
	global_load_dword v144, v[4:5], off
	s_waitcnt vmcnt(22)
	v_mfma_f32_16x16x32_bf16 v[0:3], v[16:19], v[8:11], v[24:27]
	s_lshl_b32 s14, s19, 5
	s_waitcnt vmcnt(21)
	v_mfma_f32_16x16x32_bf16 v[8:11], v[20:23], v[12:15], v[0:3]
	s_waitcnt vmcnt(14)
	v_pk_mul_f32 v[14:15], v[108:109], v[106:107] op_sel_hi:[0,1]
	v_pk_mul_f32 v[12:13], v[108:109], v[104:105] op_sel_hi:[0,1]
	s_nop 1
	v_cvt_pk_bf16_f32 v0, v104, s0
	ds_write_b16 v212, v0
	s_nop 0
	v_cvt_pk_bf16_f32 v0, v8, s0
	ds_write_b16 v212, v0 offset:4352
	v_cvt_pk_bf16_f32 v0, v105, s0
	ds_write_b16 v212, v0 offset:272
	v_cvt_pk_bf16_f32 v0, v9, s0
	ds_write_b16 v212, v0 offset:4624
	v_cvt_pk_bf16_f32 v0, v106, s0
	ds_write_b16 v212, v0 offset:544
	v_cvt_pk_bf16_f32 v0, v10, s0
	ds_write_b16 v212, v0 offset:4896
	v_cvt_pk_bf16_f32 v0, v107, s0
	ds_write_b16 v212, v0 offset:816
	v_cvt_pk_bf16_f32 v0, v11, s0
	ds_write_b16 v212, v0 offset:5168
	v_lshl_add_u64 v[0:1], v[178:179], 0, s[24:25]
	s_add_i32 s24, s26, s12
	s_ashr_i32 s25, s24, 31
	s_lshl_b64 s[24:25], s[24:25], 15
	s_add_u32 s24, s54, s24
	v_mfma_f32_16x16x32_bf16 v[12:15], v[76:79], v[72:75], v[12:15]
	v_mul_f32_e64 v10, v108, v10
	v_mul_f32_e64 v11, v108, v11
	v_pk_mul_f32 v[8:9], v[108:109], v[8:9] op_sel_hi:[0,1]
	s_waitcnt lgkmcnt(0)
	s_waitcnt vmcnt(11)
	s_barrier
; __device__ __forceinline__ void gla_scan(LAS unsigned char* lds, int bx, int G, const bf16_t* KS, const bf16_t* QD, const bf16_t* VT, const float* DEC, bf16_t* Of, bf16_t* Ob) {
;     ...
;         GLB_LOAD(0, a_); GLB_LOAD(1, b_); GLB_LOAD(2, c_);
;         GLB_LOAD(3, d_); GLB_STEP(0, a_, false);
;         GLB_LOAD(4, a_); GLB_STEP(1, b_, false);
;         GLB_LOAD(5, b_); GLB_STEP(2, c_, false);
;         GLB_LOAD(6, c_); GLB_STEP(3, d_, false);
	ds_read_b128 v[100:103], v250 offset:8192
	ds_read_b128 v[96:99], v250 offset:9216
	ds_read_b128 v[68:71], v250 offset:10240
	ds_read_b128 v[64:67], v250 offset:11264
	s_waitcnt lgkmcnt(0)
	s_addc_u32 s25, s55, s25
	s_add_i32 s15, s26, -4
	v_mfma_f32_16x16x32_bf16 v[8:11], v[84:87], v[72:75], v[8:11]
	global_load_dwordx4 v[44:47], v[0:1], off
	global_load_dwordx4 v[28:31], v[0:1], off offset:1024
	v_lshl_add_u32 v0, s22, 7, v193
	s_add_i32 s22, s15, s14
	s_ashr_i32 s23, s22, 31
	s_lshl_b64 s[22:23], s[22:23], 14
	s_lshl_b32 s18, s18, 3
	v_mfma_f32_16x16x32_bf16 v[104:107], v[80:83], v[92:95], v[12:15]
	v_lshl_add_u64 v[2:3], v[180:181], 0, s[22:23]
	s_add_i32 s22, s15, s13
	s_and_b32 s18, s18, 24
	v_mfma_f32_16x16x32_bf16 v[108:111], v[88:91], v[92:95], v[8:11]
	s_ashr_i32 s23, s22, 31
	s_or_b32 s18, s18, s16
	v_ashrrev_i32_e32 v1, 31, v0
	s_lshl_b64 s[22:23], s[22:23], 17
	s_lshl_b32 s19, s18, 12
	v_lshl_add_u64 v[0:1], v[0:1], 2, s[2:3]
	s_or_b32 s16, s22, s19
	v_cvt_pk_bf16_f32 v8, v104, s0
	v_add_u32_e32 v246, v182, v248
	s_mov_b32 m0, s98
	s_nop 0
	global_load_lds_dwordx4 v246, s[24:25]
	global_load_dword v251, v249, s[54:55]
	global_load_dword v251, v249, s[54:55]
	global_load_dword v251, v249, s[54:55]
	global_load_dword v192, v[0:1], off
	global_load_dwordx4 v[32:35], v[2:3], off
	global_load_dwordx4 v[24:27], v[2:3], off offset:1024
	global_load_dwordx4 v[4:7], v[2:3], off offset:2048
	s_nop 0
	global_load_dwordx4 v[0:3], v[2:3], off offset:3072
	s_add_u32 s16, s8, s16
	ds_write_b16 v212, v8 offset:8704
	v_cvt_pk_bf16_f32 v8, v108, s0
	s_addc_u32 s21, s9, s23
	ds_write_b16 v212, v8 offset:13056
	v_cvt_pk_bf16_f32 v8, v105, s0
	s_add_u32 s22, s16, s4
	ds_write_b16 v212, v8 offset:8976
	v_cvt_pk_bf16_f32 v8, v109, s0
	s_addc_u32 s23, s21, s5
	ds_write_b16 v212, v8 offset:13328
	v_cvt_pk_bf16_f32 v8, v106, s0
	v_lshl_add_u64 v[12:13], s[22:23], 0, v[176:177]
	ds_write_b16 v212, v8 offset:9248
	v_cvt_pk_bf16_f32 v8, v110, s0
	s_add_i32 s22, s11, s20
	ds_write_b16 v212, v8 offset:13600
	v_cvt_pk_bf16_f32 v8, v107, s0
	s_ashr_i32 s23, s22, 31
	s_waitcnt vmcnt(18)
	v_pk_mul_f32 v[106:107], v[112:113], v[106:107] op_sel_hi:[0,1]
	v_pk_mul_f32 v[104:105], v[112:113], v[104:105] op_sel_hi:[0,1]
	ds_write_b16 v212, v8 offset:9520
	v_cvt_pk_bf16_f32 v8, v111, s0
	s_lshl_b64 s[24:25], s[22:23], 14
	v_mfma_f32_16x16x32_bf16 v[100:103], v[100:103], v[60:63], v[104:107]
	ds_write_b16 v212, v8 offset:13872
	v_lshl_add_u64 v[8:9], v[178:179], 0, s[24:25]
	s_add_i32 s24, s20, s12
	s_ashr_i32 s25, s24, 31
	s_lshl_b64 s[24:25], s[24:25], 15
	s_add_u32 s24, s54, s24
	v_mfma_f32_16x16x32_bf16 v[146:149], v[96:99], v[56:59], v[100:103]
	v_mul_f32_e64 v98, v112, v110
	v_mul_f32_e64 v99, v112, v111
	v_pk_mul_f32 v[96:97], v[112:113], v[108:109] op_sel_hi:[0,1]
	s_addc_u32 s25, s55, s25
	s_add_i32 s16, s20, -4
	v_mfma_f32_16x16x32_bf16 v[60:63], v[68:71], v[60:63], v[96:99]
	s_add_i32 s20, s16, s14
	s_ashr_i32 s21, s20, 31
	s_lshl_b64 s[20:21], s[20:21], 14
	global_load_dwordx2 v[196:197], v[12:13], off
	s_waitcnt lgkmcnt(0)
	s_barrier
	v_lshl_add_u64 v[10:11], v[180:181], 0, s[20:21]
	s_add_i32 s20, s16, s13
	v_mfma_f32_16x16x32_bf16 v[150:153], v[64:67], v[56:59], v[60:63]
	global_load_dwordx4 v[76:79], v[8:9], off
	global_load_dwordx4 v[72:75], v[8:9], off offset:1024
	v_lshl_add_u32 v8, s22, 7, v193
	s_ashr_i32 s21, s20, 31
	v_ashrrev_i32_e32 v9, 31, v8
	s_lshl_b64 s[20:21], s[20:21], 17
	v_lshl_add_u64 v[8:9], v[8:9], 2, s[2:3]
	s_or_b32 s20, s20, s19
	v_cvt_pk_bf16_f32 v56, v146, s0
	v_add_u32_e32 v246, v182, v248
	s_mov_b32 m0, s99
	s_nop 0
	global_load_lds_dwordx4 v246, s[24:25]
	global_load_dword v251, v249, s[54:55]
	global_load_dword v251, v249, s[54:55]
	global_load_dword v251, v249, s[54:55]
	global_load_dword v188, v[8:9], off
	global_load_dwordx4 v[20:23], v[10:11], off
	global_load_dwordx4 v[16:19], v[10:11], off offset:1024
	global_load_dwordx4 v[12:15], v[10:11], off offset:2048
	s_nop 0
	global_load_dwordx4 v[8:11], v[10:11], off offset:3072
	s_add_u32 s20, s8, s20
	ds_write_b16 v212, v56
	v_cvt_pk_bf16_f32 v56, v150, s0
	s_addc_u32 s21, s9, s21
	ds_write_b16 v212, v56 offset:4352
	v_cvt_pk_bf16_f32 v56, v147, s0
	s_add_u32 s20, s20, s4
	ds_write_b16 v212, v56 offset:272
	v_cvt_pk_bf16_f32 v56, v151, s0
	s_addc_u32 s21, s21, s5
	ds_write_b16 v212, v56 offset:4624
	v_cvt_pk_bf16_f32 v56, v148, s0
	v_lshl_add_u64 v[68:69], s[20:21], 0, v[176:177]
	ds_write_b16 v212, v56 offset:544
	v_cvt_pk_bf16_f32 v56, v152, s0
	s_add_i32 s20, s11, s17
	ds_write_b16 v212, v56 offset:4896
	v_cvt_pk_bf16_f32 v56, v149, s0
	s_ashr_i32 s21, s20, 31
	ds_write_b16 v212, v56 offset:816
	v_cvt_pk_bf16_f32 v56, v153, s0
	s_lshl_b64 s[22:23], s[20:21], 14
	ds_write_b16 v212, v56 offset:5168
	v_lshl_add_u64 v[56:57], v[178:179], 0, s[22:23]
	s_add_i32 s22, s17, s12
	s_ashr_i32 s23, s22, 31
	s_lshl_b64 s[22:23], s[22:23], 15
	s_add_u32 s22, s54, s22
	global_load_dwordx2 v[194:195], v[68:69], off
	s_waitcnt lgkmcnt(0)
	s_waitcnt vmcnt(29)
	s_barrier
; __device__ __forceinline__ void gla_scan(LAS unsigned char* lds, int bx, int G, const bf16_t* KS, const bf16_t* QD, const bf16_t* VT, const float* DEC, bf16_t* Of, bf16_t* Ob) {
;     ...
;         GLB_LOAD(0, a_); GLB_LOAD(1, b_); GLB_LOAD(2, c_);
;         GLB_LOAD(3, d_); GLB_STEP(0, a_, false);
;         GLB_LOAD(4, a_); GLB_STEP(1, b_, false);
;         GLB_LOAD(5, b_); GLB_STEP(2, c_, false);
;         GLB_LOAD(6, c_); GLB_STEP(3, d_, false);
; #pragma unroll 1
;         for (int step = 4; step < GLA_NCH; step += 4) {
;             GLB_LOAD(step + 3, d_); GLB_STEP(step, a_, true);
;             GLB_LOAD(step + 4, a_); GLB_STEP(step + 1, b_, true);
;             GLB_LOAD(step + 5, b_); GLB_STEP(step + 2, c_, true);
;             GLB_LOAD(step + 6, c_); GLB_STEP(step + 3, d_, true);
;         }
	ds_read_b128 v[140:143], v250 offset:12288
	ds_read_b128 v[132:135], v250 offset:13312
	ds_read_b128 v[128:131], v250 offset:14336
	ds_read_b128 v[124:127], v250 offset:15360
	s_waitcnt lgkmcnt(0)
	s_addc_u32 s23, s55, s23
	s_add_i32 s17, s17, -4
	global_load_dwordx4 v[108:111], v[56:57], off
	global_load_dwordx4 v[96:99], v[56:57], off offset:1024
	v_lshl_add_u32 v56, s20, 7, v193
	s_add_i32 s20, s17, s14
	s_ashr_i32 s21, s20, 31
	s_lshl_b64 s[20:21], s[20:21], 14
	v_lshl_add_u64 v[68:69], v[180:181], 0, s[20:21]
	s_add_i32 s20, s17, s13
	s_ashr_i32 s21, s20, 31
	s_lshl_b64 s[20:21], s[20:21], 17
	s_or_b32 s19, s20, s19
	s_waitcnt vmcnt(26)
	v_pk_mul_f32 v[148:149], v[144:145], v[148:149] op_sel_hi:[0,1]
	v_pk_mul_f32 v[146:147], v[144:145], v[146:147] op_sel_hi:[0,1]
	v_ashrrev_i32_e32 v57, 31, v56
	s_add_u32 s19, s8, s19
	v_mfma_f32_16x16x32_bf16 v[140:143], v[140:143], v[120:123], v[146:149]
	v_lshl_add_u64 v[56:57], v[56:57], 2, s[2:3]
	s_addc_u32 s21, s9, s21
	global_load_dwordx4 v[116:119], v182, s[22:23]
	global_load_dwordx4 v[100:103], v182, s[22:23] offset:1024
	global_load_dwordx4 v[112:115], v182, s[22:23] offset:2048
	global_load_dwordx4 v[104:107], v182, s[22:23] offset:3072
	global_load_dword v190, v[56:57], off
	global_load_dwordx4 v[64:67], v[68:69], off
	global_load_dwordx4 v[60:63], v[68:69], off offset:1024
	s_nop 0
	global_load_dwordx4 v[56:59], v[68:69], off offset:2048
	s_nop 0
	global_load_dwordx4 v[68:71], v[68:69], off offset:3072
	s_add_u32 s20, s19, s4
	s_addc_u32 s21, s21, s5
	v_mfma_f32_16x16x32_bf16 v[156:159], v[132:135], v[136:139], v[140:143]
	v_mul_f32_e64 v134, v144, v152
	v_mul_f32_e64 v135, v144, v153
	v_pk_mul_f32 v[132:133], v[144:145], v[150:151] op_sel_hi:[0,1]
	v_lshl_add_u64 v[140:141], s[20:21], 0, v[176:177]
	global_load_dwordx2 v[160:161], v[140:141], off
	v_mfma_f32_16x16x32_bf16 v[120:123], v[128:131], v[120:123], v[132:135]
	v_mfma_f32_16x16x32_bf16 v[144:147], v[124:127], v[136:139], v[120:123]
	s_nop 6
	v_cvt_pk_bf16_f32 v120, v156, s0
	ds_write_b16 v212, v120 offset:8704
	v_cvt_pk_bf16_f32 v120, v144, s0
	ds_write_b16 v212, v120 offset:13056
	v_cvt_pk_bf16_f32 v120, v157, s0
	ds_write_b16 v212, v120 offset:8976
	v_cvt_pk_bf16_f32 v120, v145, s0
	ds_write_b16 v212, v120 offset:13328
	v_cvt_pk_bf16_f32 v120, v158, s0
	ds_write_b16 v212, v120 offset:9248
	v_cvt_pk_bf16_f32 v120, v146, s0
	ds_write_b16 v212, v120 offset:13600
	v_cvt_pk_bf16_f32 v120, v159, s0
	ds_write_b16 v212, v120 offset:9520
	v_cvt_pk_bf16_f32 v120, v147, s0
	ds_write_b16 v212, v120 offset:13872
	s_waitcnt lgkmcnt(0)
	s_waitcnt vmcnt(21)
	s_barrier
	ds_read_b128 v[48:51], v250 offset:0
	ds_read_b128 v[36:39], v250 offset:1024
	ds_read_b128 v[52:55], v250 offset:2048
	ds_read_b128 v[40:43], v250 offset:3072
	ds_read_b128 v[88:91], v250 offset:4096
	ds_read_b128 v[80:83], v250 offset:5120
	ds_read_b128 v[92:95], v250 offset:6144
	ds_read_b128 v[84:87], v250 offset:7168
	s_waitcnt lgkmcnt(0)
	v_lshl_add_u64 v[120:121], s[8:9], 0, v[176:177]
	v_lshl_add_u64 v[186:187], v[120:121], 0, s[4:5]
	s_lshl_b32 s8, s18, 12
	s_mov_b32 s9, 32
	s_mov_b32 s18, 4
.LBB0_1281:
	s_add_i32 s19, s18, 3
	s_waitcnt vmcnt(29)
	v_pk_mul_f32 v[130:131], v[158:159], v[192:193] op_sel_hi:[1,0]
	v_pk_mul_f32 v[128:129], v[156:157], v[192:193] op_sel_hi:[1,0]
	v_pk_mul_f32 v[134:135], v[146:147], v[192:193] op_sel_hi:[1,0]
	v_pk_mul_f32 v[132:133], v[144:145], v[192:193] op_sel_hi:[1,0]
	s_and_b64 s[20:21], s[6:7], exec
	v_mfma_f32_16x16x32_bf16 v[48:51], v[48:51], v[44:47], v[128:131]
	s_cselect_b32 s21, s19, s9
	s_add_i32 s22, s21, s11
	s_add_i32 s24, s21, s12
	v_mfma_f32_16x16x32_bf16 v[44:47], v[52:55], v[44:47], v[132:135]
	s_ashr_i32 s23, s22, 31
	ds_read_b128 v[172:175], v210 offset:8704
	ds_read_b128 v[140:143], v210 offset:8768
	ds_read_b128 v[124:127], v210 offset:8832
	ds_read_b128 v[120:123], v210 offset:8896
	s_add_i32 s20, s15, s13
	s_add_i32 s15, s21, -4
	s_ashr_i32 s25, s24, 31
	v_lshl_add_u32 v52, s22, 7, v193
	s_lshl_b64 s[22:23], s[22:23], 14
	s_add_i32 s26, s15, s14
	s_lshl_b64 s[24:25], s[24:25], 15
	v_mfma_f32_16x16x32_bf16 v[36:39], v[36:39], v[28:31], v[48:51]
	s_waitcnt vmcnt(0)
	v_lshlrev_b32_e32 v206, 16, v160
	v_and_b32_e32 v207, 0xffff0000, v160
	v_lshlrev_b32_e32 v208, 16, v161
	v_mfma_f32_16x16x32_bf16 v[28:31], v[40:43], v[28:31], v[44:47]
	v_lshl_add_u64 v[40:41], v[178:179], 0, s[22:23]
	v_and_b32_e32 v209, 0xffff0000, v161
	s_add_i32 s28, s15, s13
	v_ashrrev_i32_e32 v53, 31, v52
	s_ashr_i32 s27, s26, 31
	v_lshl_add_u64 v[42:43], v[184:185], 0, s[24:25]
	global_load_dwordx4 v[160:163], v[40:41], off
	global_load_dwordx4 v[144:147], v[40:41], off offset:1024
	v_lshl_add_u64 v[246:247], v[42:43], 0, v[248:249]
	s_mov_b32 m0, s101
	s_nop 0
	global_load_lds_dwordx4 v[246:247], off
	global_load_dword v251, v249, s[54:55]
	global_load_dword v251, v249, s[54:55]
	global_load_dword v251, v249, s[54:55]
	s_waitcnt lgkmcnt(3)
	v_mfma_f32_16x16x32_bf16 v[32:35], v[172:175], v[32:35], 0
	s_ashr_i32 s21, s20, 31
	s_ashr_i32 s29, s28, 31
	v_lshl_add_u64 v[44:45], v[52:53], 2, s[2:3]
	s_lshl_b64 s[22:23], s[26:27], 14
	s_lshl_b64 s[20:21], s[20:21], 17
	s_lshl_b64 s[24:25], s[28:29], 17
	v_lshl_add_u64 v[40:41], v[180:181], 0, s[22:23]
	global_load_dword v182, v[44:45], off
	global_load_dwordx4 v[152:155], v[40:41], off
	global_load_dwordx4 v[136:139], v[40:41], off offset:1024
	global_load_dwordx4 v[132:135], v[40:41], off offset:2048
	global_load_dwordx4 v[128:131], v[40:41], off offset:3072
	s_add_i32 s19, s18, 4
	s_or_b32 s20, s20, s8
	s_or_b32 s24, s24, s8
	s_cmp_lt_u32 s18, 32
	s_waitcnt lgkmcnt(2)
; __device__ __forceinline__ void gla_scan(LAS unsigned char* lds, int bx, int G, const bf16_t* KS, const bf16_t* QD, const bf16_t* VT, const float* DEC, bf16_t* Of, bf16_t* Ob) {
;     ...
;         __syncthreads();
;         GLB_LOAD(0, a_); GLB_LOAD(1, b_); GLB_LOAD(2, c_);
;         GLB_LOAD(3, d_); GLB_STEP(0, a_, false);
;         GLB_LOAD(4, a_); GLB_STEP(1, b_, false);
;         GLB_LOAD(5, b_); GLB_STEP(2, c_, false);
;         GLB_LOAD(6, c_); GLB_STEP(3, d_, false);
; #pragma unroll 1
;         for (int step = 4; step < GLA_NCH; step += 4) {
;             GLB_LOAD(step + 3, d_); GLB_STEP(step, a_, true);
;             GLB_LOAD(step + 4, a_); GLB_STEP(step + 1, b_, true);
;             GLB_LOAD(step + 5, b_); GLB_STEP(step + 2, c_, true);
;             GLB_LOAD(step + 6, c_); GLB_STEP(step + 3, d_, true);
;         }
	v_mfma_f32_16x16x32_bf16 v[24:27], v[140:143], v[24:27], v[32:35]
	s_cselect_b32 s15, s19, 35
	v_cvt_pk_bf16_f32 v40, v36, s0
	v_cvt_pk_bf16_f32 v41, v28, s0
	v_cvt_pk_bf16_f32 v42, v37, s0
	v_cvt_pk_bf16_f32 v43, v29, s0
	v_cvt_pk_bf16_f32 v44, v38, s0
	v_cvt_pk_bf16_f32 v45, v30, s0
	v_cvt_pk_bf16_f32 v48, v39, s0
	v_cvt_pk_bf16_f32 v49, v31, s0
	v_pk_mul_f32 v[38:39], v[188:189], v[38:39] op_sel_hi:[0,1]
	v_pk_mul_f32 v[36:37], v[188:189], v[36:37] op_sel_hi:[0,1]
	v_pk_mul_f32 v[30:31], v[188:189], v[30:31] op_sel_hi:[0,1]
	v_pk_mul_f32 v[28:29], v[188:189], v[28:29] op_sel_hi:[0,1]
	s_sub_i32 s22, 39, s15
	v_lshl_add_u64 v[46:47], v[186:187], 0, s[20:21]
	v_mfma_f32_16x16x32_bf16 v[36:39], v[88:91], v[76:79], v[36:39]
	s_and_b64 s[20:21], s[6:7], exec
	v_lshl_add_u64 v[200:201], v[186:187], 0, s[24:25]
	s_cselect_b32 s15, s15, s22
	v_mfma_f32_16x16x32_bf16 v[28:31], v[92:95], v[76:79], v[28:31]
	global_load_dwordx2 v[204:205], v[200:201], off
	ds_write_b16 v212, v40
	ds_write_b16 v212, v41 offset:4352
	ds_write_b16 v212, v42 offset:272
	ds_write_b16 v212, v43 offset:4624
	ds_write_b16 v212, v44 offset:544
	ds_write_b16 v212, v45 offset:4896
	s_add_i32 s20, s16, s13
	s_waitcnt lgkmcnt(7)
	v_mfma_f32_16x16x32_bf16 v[4:7], v[124:127], v[4:7], v[24:27]
	v_sub_u32_e64 v41, s15, 4 clamp
	s_add_i32 s22, s15, s11
	s_add_i32 s24, s15, s12
	s_ashr_i32 s21, s20, 31
	v_readfirstlane_b32 s15, v41
	v_mfma_f32_16x16x32_bf16 v[32:35], v[80:83], v[72:75], v[36:39]
	s_lshl_b64 s[20:21], s[20:21], 17
	s_add_i32 s26, s15, s13
	s_or_b32 s20, s20, s8
	v_mfma_f32_16x16x32_bf16 v[28:31], v[84:87], v[72:75], v[28:31]
	s_ashr_i32 s27, s26, 31
	s_min_u32 s16, s18, 30
	s_ashr_i32 s23, s22, 31
	s_waitcnt lgkmcnt(6)
	v_mfma_f32_16x16x32_bf16 v[0:3], v[120:123], v[0:3], v[4:7]
	s_ashr_i32 s25, s24, 31
	v_add_u32_e32 v40, s14, v41
	v_lshl_add_u64 v[88:89], v[186:187], 0, s[20:21]
	s_lshl_b64 s[20:21], s[26:27], 17
	s_add_i32 s28, s16, 5
	s_sub_i32 s16, 34, s16
	v_lshl_add_u32 v36, s22, 7, v193
	s_lshl_b64 s[22:23], s[22:23], 14
	s_lshl_b64 s[24:25], s[24:25], 15
	v_ashrrev_i32_e32 v41, 31, v40
	s_or_b32 s20, s20, s8
	v_lshlrev_b32_e32 v198, 16, v196
	v_and_b32_e32 v199, 0xffff0000, v196
	v_lshlrev_b32_e32 v196, 16, v197
	v_and_b32_e32 v197, 0xffff0000, v197
	v_lshlrev_b64 v[38:39], 14, v[40:41]
	v_lshl_add_u64 v[40:41], v[178:179], 0, s[22:23]
	v_cvt_pk_bf16_f32 v93, v28, s0
	v_cvt_pk_bf16_f32 v95, v29, s0
	v_cvt_pk_bf16_f32 v141, v30, s0
	v_cvt_pk_bf16_f32 v143, v31, s0
	v_pk_mul_f32 v[26:27], v[190:191], v[34:35] op_sel_hi:[0,1]
	v_pk_mul_f32 v[24:25], v[190:191], v[32:33] op_sel_hi:[0,1]
	v_pk_mul_f32 v[30:31], v[190:191], v[30:31] op_sel_hi:[0,1]
	v_pk_mul_f32 v[28:29], v[190:191], v[28:29] op_sel_hi:[0,1]
	s_and_b64 s[22:23], s[6:7], exec
	v_mfma_f32_16x16x32_bf16 v[24:27], v[116:119], v[108:111], v[24:27]
	s_cselect_b32 s16, s28, s16
	v_pk_add_f32 v[2:3], v[2:3], v[196:197]
	v_pk_add_f32 v[0:1], v[0:1], v[198:199]
	v_mfma_f32_16x16x32_bf16 v[28:31], v[112:115], v[108:111], v[28:31]
	s_add_i32 s22, s16, s11
	v_cvt_pk_bf16_f32 v0, v0, v1
	v_cvt_pk_bf16_f32 v1, v2, v3
	ds_write_b16 v212, v48 offset:816
	ds_write_b16 v212, v49 offset:5168
	v_ashrrev_i32_e32 v37, 31, v36
	v_lshl_add_u32 v4, s22, 7, v193
	global_store_dwordx2 v[46:47], v[0:1], off
	v_lshl_add_u64 v[42:43], v[184:185], 0, s[24:25]
	v_lshl_add_u64 v[72:73], v[36:37], 2, s[2:3]
	v_lshl_add_u64 v[74:75], v[180:181], 0, v[38:39]
	v_lshl_add_u64 v[76:77], v[186:187], 0, s[20:21]
	v_ashrrev_i32_e32 v5, 31, v4
	s_waitcnt lgkmcnt(0)
	s_barrier
	v_cvt_pk_bf16_f32 v92, v32, s0
	v_cvt_pk_bf16_f32 v94, v33, s0
	v_cvt_pk_bf16_f32 v140, v34, s0
	v_cvt_pk_bf16_f32 v142, v35, s0
	v_mfma_f32_16x16x32_bf16 v[120:123], v[100:103], v[96:99], v[24:27]
	v_lshl_add_u64 v[100:101], v[4:5], 2, s[2:3]
	s_add_i32 s24, s16, s12
	s_add_i32 s16, s16, -4
	v_mfma_f32_16x16x32_bf16 v[124:127], v[104:107], v[96:99], v[28:31]
	global_load_dwordx4 v[44:47], v[40:41], off
	s_nop 1
	global_load_dwordx4 v[28:31], v[40:41], off offset:1024
	v_lshl_add_u64 v[246:247], v[42:43], 0, v[248:249]
	s_mov_b32 m0, s98
	s_nop 0
	global_load_lds_dwordx4 v[246:247], off
	global_load_dword v251, v249, s[54:55]
	global_load_dword v251, v249, s[54:55]
	s_nop 0
	global_load_dword v251, v249, s[54:55]
	s_nop 0
	global_load_dword v192, v[72:73], off
	global_load_dwordx4 v[32:35], v[74:75], off
	global_load_dwordx4 v[24:27], v[74:75], off offset:1024
	global_load_dwordx4 v[4:7], v[74:75], off offset:2048
	global_load_dwordx4 v[0:3], v[74:75], off offset:3072
	global_load_dwordx2 v[196:197], v[76:77], off
	ds_read_b128 v[72:75], v210
	ds_read_b128 v[76:79], v210 offset:64
	ds_read_b128 v[80:83], v210 offset:128
	ds_read_b128 v[84:87], v210 offset:192
	s_add_i32 s20, s17, s13
	s_waitcnt lgkmcnt(3)
	v_mfma_f32_16x16x32_bf16 v[20:23], v[72:75], v[20:23], 0
	s_add_i32 s28, s16, s13
	s_ashr_i32 s21, s20, 31
	s_add_i32 s26, s16, s14
	s_waitcnt lgkmcnt(2)
	v_mfma_f32_16x16x32_bf16 v[16:19], v[76:79], v[16:19], v[20:23]
	s_ashr_i32 s29, s28, 31
	s_min_u32 s17, s18, 29
	s_ashr_i32 s23, s22, 31
	s_waitcnt lgkmcnt(1)
	v_mfma_f32_16x16x32_bf16 v[12:15], v[80:83], v[12:15], v[16:19]
	s_ashr_i32 s25, s24, 31
	s_lshl_b64 s[20:21], s[20:21], 17
	s_ashr_i32 s27, s26, 31
	s_waitcnt lgkmcnt(0)
	v_mfma_f32_16x16x32_bf16 v[8:11], v[84:87], v[8:11], v[12:15]
	s_lshl_b64 s[28:29], s[28:29], 17
	s_add_i32 s30, s17, 6
	s_sub_i32 s17, 33, s17
	s_lshl_b64 s[22:23], s[22:23], 14
	s_lshl_b64 s[24:25], s[24:25], 15
	s_or_b32 s20, s20, s8
	s_lshl_b64 s[26:27], s[26:27], 14
	s_or_b32 s28, s28, s8
	v_lshlrev_b32_e32 v202, 16, v194
	v_and_b32_e32 v203, 0xffff0000, v194
	v_lshlrev_b32_e32 v194, 16, v195
	v_and_b32_e32 v195, 0xffff0000, v195
	v_lshl_add_u64 v[108:109], v[186:187], 0, s[20:21]
	s_and_b64 s[20:21], s[6:7], exec
	s_cselect_b32 s17, s30, s17
	v_pk_add_f32 v[10:11], v[10:11], v[194:195]
	v_pk_add_f32 v[8:9], v[8:9], v[202:203]
	s_add_i32 s20, s17, s11
	v_cvt_pk_bf16_f32 v8, v8, v9
	v_cvt_pk_bf16_f32 v9, v10, v11
	ds_write_b16 v212, v92 offset:8704
	ds_write_b16 v212, v93 offset:13056
	ds_write_b16 v212, v94 offset:8976
	ds_write_b16 v212, v95 offset:13328
	ds_write_b16 v212, v140 offset:9248
	ds_write_b16 v212, v141 offset:13600
	ds_write_b16 v212, v142 offset:9520
	ds_write_b16 v212, v143 offset:13872
	v_lshl_add_u32 v92, s20, 7, v193
	global_store_dwordx2 v[88:89], v[8:9], off
	v_lshl_add_u64 v[90:91], v[178:179], 0, s[22:23]
	v_lshl_add_u64 v[96:97], v[184:185], 0, s[24:25]
	v_ashrrev_i32_e32 v93, 31, v92
	s_waitcnt lgkmcnt(0)
	s_barrier
; __device__ __forceinline__ void gla_scan(LAS unsigned char* lds, int bx, int G, const bf16_t* KS, const bf16_t* QD, const bf16_t* VT, const float* DEC, bf16_t* Of, bf16_t* Ob) {
;     ...
;         __syncthreads();
;         GLB_LOAD(0, a_); GLB_LOAD(1, b_); GLB_LOAD(2, c_);
;         GLB_LOAD(3, d_); GLB_STEP(0, a_, false);
;         GLB_LOAD(4, a_); GLB_STEP(1, b_, false);
;         GLB_LOAD(5, b_); GLB_STEP(2, c_, false);
;         GLB_LOAD(6, c_); GLB_STEP(3, d_, false);
; #pragma unroll 1
;         for (int step = 4; step < GLA_NCH; step += 4) {
;             GLB_LOAD(step + 3, d_); GLB_STEP(step, a_, true);
;             GLB_LOAD(step + 4, a_); GLB_STEP(step + 1, b_, true);
;             GLB_LOAD(step + 5, b_); GLB_STEP(step + 2, c_, true);
;             GLB_LOAD(step + 6, c_); GLB_STEP(step + 3, d_, true);
	v_lshl_add_u64 v[142:143], v[92:93], 2, s[2:3]
	global_load_dwordx4 v[76:79], v[90:91], off
	global_load_dwordx4 v[72:75], v[90:91], off offset:1024
	s_nop 0
	v_lshl_add_u64 v[246:247], v[96:97], 0, v[248:249]
	s_mov_b32 m0, s99
	s_nop 0
	global_load_lds_dwordx4 v[246:247], off
	global_load_dword v251, v249, s[54:55]
	global_load_dword v251, v249, s[54:55]
	global_load_dword v251, v249, s[54:55]
	ds_read_b128 v[96:99], v210 offset:8704
	v_lshl_add_u64 v[104:105], v[180:181], 0, s[26:27]
	global_load_dword v188, v[100:101], off
	global_load_dwordx4 v[20:23], v[104:105], off
	ds_read_b128 v[100:103], v210 offset:8768
	v_lshl_add_u64 v[106:107], v[186:187], 0, s[28:29]
	global_load_dwordx4 v[16:19], v[104:105], off offset:1024
	global_load_dwordx4 v[12:15], v[104:105], off offset:2048
	global_load_dwordx4 v[8:11], v[104:105], off offset:3072
	global_load_dwordx2 v[194:195], v[106:107], off
	ds_read_b128 v[104:107], v210 offset:8832
	s_waitcnt lgkmcnt(2)
	v_mfma_f32_16x16x32_bf16 v[64:67], v[96:99], v[64:67], 0
	ds_read_b128 v[96:99], v210 offset:8896
	s_add_i32 s22, s17, s12
	s_add_i32 s17, s17, -4
	s_waitcnt lgkmcnt(2)
	v_mfma_f32_16x16x32_bf16 v[60:63], v[100:103], v[60:63], v[64:67]
	v_cvt_pk_bf16_f32 v110, v120, s0
	v_cvt_pk_bf16_f32 v114, v121, s0
	v_cvt_pk_bf16_f32 v117, v126, s0
	s_waitcnt lgkmcnt(1)
	v_mfma_f32_16x16x32_bf16 v[56:59], v[104:107], v[56:59], v[60:63]
	s_ashr_i32 s21, s20, 31
	s_add_i32 s24, s17, s14
	v_cvt_pk_bf16_f32 v111, v124, s0
	s_waitcnt lgkmcnt(0)
	v_mfma_f32_16x16x32_bf16 v[56:59], v[96:99], v[68:71], v[56:59]
	v_cvt_pk_bf16_f32 v115, v125, s0
	v_cvt_pk_bf16_f32 v116, v122, s0
	v_cvt_pk_bf16_f32 v118, v123, s0
	v_cvt_pk_bf16_f32 v119, v127, s0
	s_ashr_i32 s23, s22, 31
	s_nop 2
	v_pk_add_f32 v[58:59], v[58:59], v[208:209]
	v_pk_add_f32 v[56:57], v[56:57], v[206:207]
	s_lshl_b64 s[20:21], s[20:21], 14
	v_cvt_pk_bf16_f32 v56, v56, v57
	v_cvt_pk_bf16_f32 v57, v58, v59
	s_ashr_i32 s25, s24, 31
	ds_write_b16 v212, v110
	ds_write_b16 v212, v111 offset:4352
	ds_write_b16 v212, v114 offset:272
	ds_write_b16 v212, v115 offset:4624
	ds_write_b16 v212, v116 offset:544
	ds_write_b16 v212, v117 offset:4896
	ds_write_b16 v212, v118 offset:816
	ds_write_b16 v212, v119 offset:5168
	global_store_dwordx2 v[108:109], v[56:57], off
	s_lshl_b64 s[22:23], s[22:23], 15
	s_lshl_b64 s[24:25], s[24:25], 14
	v_lshl_add_u64 v[112:113], v[178:179], 0, s[20:21]
	s_waitcnt lgkmcnt(0)
	s_waitcnt vmcnt(36)
	s_barrier
	ds_read_b128 v[168:171], v250 offset:12288
	ds_read_b128 v[156:159], v250 offset:13312
	ds_read_b128 v[164:167], v250 offset:14336
	ds_read_b128 v[148:151], v250 offset:15360
	s_waitcnt lgkmcnt(0)
	v_lshl_add_u64 v[140:141], v[184:185], 0, s[22:23]
	v_lshl_add_u64 v[172:173], v[180:181], 0, s[24:25]
	global_load_dwordx4 v[108:111], v[112:113], off
	global_load_dwordx4 v[96:99], v[112:113], off offset:1024
	global_load_dwordx4 v[116:119], v[140:141], off
	global_load_dwordx4 v[100:103], v[140:141], off offset:1024
	s_nop 0
	global_load_dwordx4 v[112:115], v[140:141], off offset:2048
	global_load_dwordx4 v[104:107], v[140:141], off offset:3072
	global_load_dword v190, v[142:143], off
	global_load_dwordx4 v[64:67], v[172:173], off
	global_load_dwordx4 v[60:63], v[172:173], off offset:1024
	global_load_dwordx4 v[56:59], v[172:173], off offset:2048
	s_add_i32 s26, s17, s13
	s_ashr_i32 s27, s26, 31
	s_lshl_b64 s[26:27], s[26:27], 17
	s_or_b32 s26, s26, s8
	v_lshl_add_u64 v[174:175], v[186:187], 0, s[26:27]
	s_waitcnt vmcnt(42)
	v_pk_mul_f32 v[70:71], v[182:183], v[122:123] op_sel_hi:[0,1]
	v_pk_mul_f32 v[68:69], v[182:183], v[120:121] op_sel_hi:[0,1]
	v_pk_mul_f32 v[126:127], v[182:183], v[126:127] op_sel_hi:[0,1]
	v_pk_mul_f32 v[124:125], v[182:183], v[124:125] op_sel_hi:[0,1]
	v_mfma_f32_16x16x32_bf16 v[120:123], v[168:171], v[160:163], v[68:71]
	s_waitcnt vmcnt(37)
	v_lshlrev_b32_e32 v170, 16, v204
	v_and_b32_e32 v171, 0xffff0000, v204
	s_add_i32 s9, s9, -4
	global_load_dwordx4 v[68:71], v[172:173], off offset:3072
	v_mfma_f32_16x16x32_bf16 v[124:127], v[164:167], v[160:163], v[124:127]
	global_load_dwordx2 v[160:161], v[174:175], off
	ds_read_b128 v[140:143], v210
	ds_read_b128 v[162:165], v210 offset:64
	s_cmp_gt_u32 s18, 31
	v_mfma_f32_16x16x32_bf16 v[156:159], v[156:159], v[144:147], v[120:123]
	s_nop 2
	ds_read_b128 v[120:123], v210 offset:128
	ds_read_b128 v[166:169], v210 offset:192
	s_mov_b32 s18, s19
	v_mfma_f32_16x16x32_bf16 v[144:147], v[148:151], v[144:147], v[124:127]
	v_lshlrev_b32_e32 v148, 16, v205
	v_and_b32_e32 v149, 0xffff0000, v205
	v_cvt_pk_bf16_f32 v150, v158, s0
	s_waitcnt lgkmcnt(3)
	v_mfma_f32_16x16x32_bf16 v[124:127], v[140:143], v[152:155], 0
	v_cvt_pk_bf16_f32 v140, v156, s0
	s_nop 1
	v_cvt_pk_bf16_f32 v151, v146, s0
	v_cvt_pk_bf16_f32 v141, v144, s0
	s_waitcnt lgkmcnt(2)
	v_mfma_f32_16x16x32_bf16 v[124:127], v[162:165], v[136:139], v[124:127]
	v_cvt_pk_bf16_f32 v142, v157, s0
	v_cvt_pk_bf16_f32 v143, v145, s0
	v_cvt_pk_bf16_f32 v152, v159, s0
	s_waitcnt lgkmcnt(1)
	v_mfma_f32_16x16x32_bf16 v[120:123], v[120:123], v[132:135], v[124:127]
	v_cvt_pk_bf16_f32 v153, v147, s0
	ds_write_b16 v212, v140 offset:8704
	ds_write_b16 v212, v141 offset:13056
	ds_write_b16 v212, v142 offset:8976
	ds_write_b16 v212, v143 offset:13328
	ds_write_b16 v212, v150 offset:9248
	ds_write_b16 v212, v151 offset:13600
	ds_write_b16 v212, v152 offset:9520
	ds_write_b16 v212, v153 offset:13872
	s_waitcnt lgkmcnt(8)
	v_mfma_f32_16x16x32_bf16 v[120:123], v[166:169], v[128:131], v[120:123]
	s_nop 7
	v_pk_add_f32 v[122:123], v[122:123], v[148:149]
	v_pk_add_f32 v[120:121], v[120:121], v[170:171]
	s_nop 0
	v_cvt_pk_bf16_f32 v120, v120, v121
	v_cvt_pk_bf16_f32 v121, v122, v123
	global_store_dwordx2 v[200:201], v[120:121], off
	s_waitcnt lgkmcnt(0)
	s_waitcnt vmcnt(23)
	s_barrier
	ds_read_b128 v[48:51], v250 offset:0
	ds_read_b128 v[36:39], v250 offset:1024
	ds_read_b128 v[52:55], v250 offset:2048
	ds_read_b128 v[40:43], v250 offset:3072
	ds_read_b128 v[88:91], v250 offset:4096
	ds_read_b128 v[80:83], v250 offset:5120
	ds_read_b128 v[92:95], v250 offset:6144
	ds_read_b128 v[84:87], v250 offset:7168
	s_waitcnt lgkmcnt(0)
	s_cbranch_scc0 .LBB0_1281
	s_add_i32 s10, s10, s34
	s_cmpk_gt_i32 s10, 0xff
	s_cbranch_scc0 .LBB0_1280
